# micro1 plus early buffer_wbl2 by wave 1 of every workgroup right after the opening barrier of each grid sync (L2 write-back overlaps arrival skew)
# baseline (speedup 1.0000x reference)
; __device__ __forceinline__ void xcd_barrier(const XcdBarrier& b) {
;     asm volatile("s_waitcnt vmcnt(0)" ::: "memory");
;     __syncthreads();
;     if (threadIdx.x == 0) {
;         unsigned* bar = b.bar;
;         __builtin_amdgcn_s_waitcnt(0);
;         unsigned nloc = b.st[0], nx = b.st[1];
;         if (nloc == 0u) { xcd_barrier_complete(bar, b.x, nloc, nx); b.st[0] = nloc; b.st[1] = nx; }
.LBB0_204:
	s_waitcnt vmcnt(0)
	s_waitcnt vmcnt(0) lgkmcnt(0)
	s_barrier
	v_readfirstlane_b32 s100, v202
	s_nop 3
	s_lshr_b32 s100, s100, 6
	s_cmp_eq_u32 s100, 1
	s_cbranch_scc0 .Lewb_lbb0_204
	buffer_wbl2 sc1
.Lewb_lbb0_204:
	s_mov_b64 s[4:5], exec
	v_readlane_b32 s6, v250, 26
	v_readlane_b32 s7, v250, 27
	s_and_b64 s[6:7], s[4:5], s[6:7]
	s_mov_b64 exec, s[6:7]
	s_cbranch_execz .LBB0_256
	v_readlane_b32 s6, v248, 10
	s_waitcnt vmcnt(0) expcnt(0) lgkmcnt(0)
	s_nop 0
	v_mov_b32_e32 v0, s6
	ds_read_b32 v2, v0
	v_readlane_b32 s6, v248, 11
	s_waitcnt lgkmcnt(0)
	v_cmp_ne_u32_e32 vcc, 0, v2
	v_mov_b32_e32 v0, s6
	ds_read_b32 v0, v0
	s_cbranch_vccnz .LBB0_220
	s_mov_b32 s14, 1
	s_branch .LBB0_208

; __device__ __forceinline__ void xcd_barrier(const XcdBarrier& b) {
;     asm volatile("s_waitcnt vmcnt(0)" ::: "memory");
;     __syncthreads();
;     if (threadIdx.x == 0) {
;         unsigned* bar = b.bar;
;         __builtin_amdgcn_s_waitcnt(0);
;         unsigned nloc = b.st[0], nx = b.st[1];
;         if (nloc == 0u) { xcd_barrier_complete(bar, b.x, nloc, nx); b.st[0] = nloc; b.st[1] = nx; }
.LBB0_306:
	s_waitcnt vmcnt(0)
	s_barrier
	v_readfirstlane_b32 s100, v202
	s_nop 3
	s_lshr_b32 s100, s100, 6
	s_cmp_eq_u32 s100, 1
	s_cbranch_scc0 .Lewb_lbb0_306
	buffer_wbl2 sc1
.Lewb_lbb0_306:
	s_mov_b64 s[4:5], exec
	v_readlane_b32 s6, v250, 26
	v_readlane_b32 s7, v250, 27
	s_and_b64 s[6:7], s[4:5], s[6:7]
	s_mov_b64 exec, s[6:7]
	s_cbranch_execz .LBB0_358
	v_readlane_b32 s6, v248, 10
	s_waitcnt vmcnt(0) expcnt(0) lgkmcnt(0)
	s_nop 0
	v_mov_b32_e32 v0, s6
	ds_read_b32 v2, v0
	v_readlane_b32 s6, v248, 11
	s_waitcnt lgkmcnt(0)
	v_cmp_ne_u32_e32 vcc, 0, v2
	v_mov_b32_e32 v0, s6
	ds_read_b32 v0, v0
	s_cbranch_vccnz .LBB0_322
	s_mov_b32 s12, 1
	s_branch .LBB0_310

; __device__ __forceinline__ void xcd_barrier(const XcdBarrier& b) {
;     asm volatile("s_waitcnt vmcnt(0)" ::: "memory");
;     __syncthreads();
.LBB0_408:
	s_waitcnt vmcnt(0)
	s_waitcnt lgkmcnt(0)
	s_barrier
	v_readfirstlane_b32 s100, v202
	s_nop 3
	s_lshr_b32 s100, s100, 6
	s_cmp_eq_u32 s100, 1
	s_cbranch_scc0 .Lewb_lbb0_408
	buffer_wbl2 sc1
